# grid barrier: released workgroups poll the cross-XCC release generation directly (one poll/atomic hop less per barrier)
# speedup vs baseline: 1.1692x; 1.0037x over previous
; __device__ __forceinline__ unsigned xb_ld(unsigned* p)              { return __hip_atomic_load(p, __ATOMIC_RELAXED, __HIP_MEMORY_SCOPE_AGENT); }
; __device__ __forceinline__ unsigned xb_add(unsigned* p, unsigned v) { return __hip_atomic_fetch_add(p, v, __ATOMIC_RELAXED, __HIP_MEMORY_SCOPE_AGENT); }
; #define XB_SPIN(cond, bar) do { unsigned _sp = 0; while (cond) { __builtin_amdgcn_s_sleep(1); \
;     if ((++_sp & 255u) == 0u) { if (xb_ld(&(bar)[XB_TMO])) break; if (_sp > XB_SPIN_CAP) { atomicAdd(&(bar)[XB_TMO], 1u); break; } } } } while (0)
; __device__ __forceinline__ void xcd_barrier(const XcdBarrier& b) {
;     ...
;         const unsigned old = xb_add(&bar[XB_XSUB(b.x)], 1u);
;         const unsigned gen = old / nloc;
;         if (old + 1u == (gen + 1u) * nloc) {
;             __builtin_amdgcn_fence(__ATOMIC_RELEASE, "agent");
;             asm volatile("s_waitcnt vmcnt(0)" ::: "memory");
;             const unsigned og = xb_add(&bar[XB_TOP], 1u);
;             const unsigned tg = og / nx;
;             if (og + 1u == (tg + 1u) * nx) xb_add(&bar[XB_TOPGEN], 1u);
;             else XB_SPIN(xb_ld(&bar[XB_TOPGEN]) == tg, bar);
;             __builtin_amdgcn_fence(__ATOMIC_ACQUIRE, "agent");
;             xb_add(&bar[XB_XGEN(b.x)], 1u);
;             asm volatile("s_waitcnt vmcnt(0)" ::: "memory");
;         } else {
;             XB_SPIN(xb_ld(&bar[XB_XGEN(b.x)]) == gen, bar);
;             __builtin_amdgcn_fence(__ATOMIC_ACQUIRE, "agent");
;             asm volatile("s_waitcnt vmcnt(0)" ::: "memory");
;         }
.LBB0_529:
	s_or_b64 exec, exec, s[6:7]
	v_cvt_f32_u32_e32 v5, v3
	s_waitcnt vmcnt(0)
	v_readfirstlane_b32 s6, v4
	v_sub_u32_e32 v4, 0, v3
	v_rcp_iflag_f32_e32 v5, v5
	v_add_u32_e32 v6, s6, v0
	v_mul_f32_e32 v5, 0x4f7ffffe, v5
	v_cvt_u32_f32_e32 v5, v5
	v_mul_lo_u32 v0, v4, v5
	v_mul_hi_u32 v0, v5, v0
	v_add_u32_e32 v0, v5, v0
	v_mul_hi_u32 v0, v6, v0
	v_mul_lo_u32 v4, v0, v3
	v_sub_u32_e32 v4, v6, v4
	v_add_u32_e32 v5, 1, v0
	v_cmp_ge_u32_e32 vcc, v4, v3
	s_nop 1
	v_cndmask_b32_e32 v0, v0, v5, vcc
	v_sub_u32_e32 v5, v4, v3
	v_cndmask_b32_e32 v4, v4, v5, vcc
	v_add_u32_e32 v5, 1, v0
	v_cmp_ge_u32_e32 vcc, v4, v3
	v_add_u32_e32 v4, 1, v6
	s_nop 0
	v_cndmask_b32_e32 v0, v0, v5, vcc
	v_mul_lo_u32 v5, v3, v0
	v_add_u32_e32 v3, v5, v3
	v_cmp_ne_u32_e32 vcc, v4, v3
	s_and_saveexec_b64 s[6:7], vcc
	s_xor_b64 s[6:7], exec, s[6:7]
	s_cbranch_execz .LBB0_544
	v_readlane_b32 s8, v255, 6
	v_readlane_b32 s9, v255, 7
	s_waitcnt lgkmcnt(0)
	s_nop 3
	global_load_dword v2, v1, s[8:9] sc1
	s_waitcnt vmcnt(0)
	v_cmp_eq_u32_e32 vcc, v2, v0
	s_and_saveexec_b64 s[8:9], vcc
	s_cbranch_execz .LBB0_543
	s_mov_b32 s29, 1
	s_mov_b64 s[18:19], 0
	s_branch .LBB0_533
